# mixA masked logits: 16 bias LDS reads per key block issued together, mask applied with v_cndmask instead of 16 exec-masked read+wait steps; on top of previous version
# baseline (speedup 1.0000x reference)
; DI int crow(int reg, int h) { return (reg & 3) + 8 * (reg >> 2) + 4 * h; }
; DI void mixA_wave_item(const Params& p, int wi, int lane, const LAS float* tb) {
;     ...
;         float mx = -INFINITY;
; #pragma unroll
;         for (int i = 0; i < 16; ++i) { const int rel = mk0r + crow(i, hh) - (m0 + r); const bool valid = blk_ok && (rel <= 64) && (rel >= -64);
;             const float bv = tbl[32 * kb + (i & 3) + 8 * (i >> 2)];
;             const float v = valid ? (s[i] * cs + bv) : -INFINITY; s[i] = v; mx = fmaxf(mx, v); }
;         mx = xhalf_max(mx);
;         const float mnew = fmaxf(m, mx), alpha = __builtin_amdgcn_exp2f(m - mnew);
;         m = mnew;
;         float rs = 0.f;
; #pragma unroll
;         for (int i = 0; i < 16; ++i) { s[i] = __builtin_amdgcn_exp2f(s[i] - mnew); rs += s[i]; }
;         lsum = lsum * alpha + rs;
.LBB0_562:
	ds_read_b32 v214, v207
	ds_read_b32 v215, v207 offset:4
	ds_read_b32 v216, v207 offset:8
	ds_read_b32 v217, v207 offset:12
	ds_read_b32 v218, v207 offset:32
	ds_read_b32 v219, v207 offset:36
	ds_read_b32 v220, v207 offset:40
	ds_read_b32 v221, v207 offset:44
	ds_read_b32 v234, v207 offset:64
	ds_read_b32 v235, v207 offset:68
	ds_read_b32 v236, v207 offset:72
	ds_read_b32 v237, v207 offset:76
	ds_read_b32 v238, v207 offset:96
	ds_read_b32 v239, v207 offset:100
	ds_read_b32 v246, v207 offset:104
	ds_read_b32 v247, v207 offset:108
	s_waitcnt lgkmcnt(0)
	v_add_u32_e32 v211, s4, v208
	v_cmp_gt_u32_e64 s[40:41], s33, v211
	s_and_b64 s[6:7], vcc, s[40:41]
	v_mov_b32_e32 v195, 0xff800000
	v_mov_b32_e32 v197, 0xff800000
	v_fmac_f32_e32 v214, 0x3e0293ee, v64
	v_cndmask_b32_e64 v197, v197, v214, s[6:7]
	v_add_u32_e32 v64, 1, v211
	v_cmp_gt_u32_e64 s[40:41], s33, v64
	s_and_b64 s[6:7], vcc, s[40:41]
	v_fmac_f32_e32 v215, 0x3e0293ee, v65
	v_cndmask_b32_e64 v195, v195, v215, s[6:7]
	v_add_u32_e32 v64, 2, v211
	v_cmp_gt_u32_e64 s[40:41], s33, v64
	s_and_b64 s[6:7], vcc, s[40:41]
	v_mov_b32_e32 v65, 0xff800000
	v_mov_b32_e32 v199, 0xff800000
	v_fmac_f32_e32 v216, 0x3e0293ee, v66
	v_cndmask_b32_e64 v199, v199, v216, s[6:7]
	v_add_u32_e32 v64, 3, v211
	v_cmp_gt_u32_e64 s[40:41], s33, v64
	s_and_b64 s[6:7], vcc, s[40:41]
	v_fmac_f32_e32 v217, 0x3e0293ee, v67
	v_cndmask_b32_e64 v65, v65, v217, s[6:7]
	v_add_u32_e32 v64, 8, v211
	v_cmp_gt_u32_e64 s[40:41], s33, v64
	s_and_b64 s[6:7], vcc, s[40:41]
	v_mov_b32_e32 v67, 0xff800000
	v_mov_b32_e32 v212, 0xff800000
	v_fmac_f32_e32 v218, 0x3e0293ee, v68
	v_cndmask_b32_e64 v212, v212, v218, s[6:7]
	v_add_u32_e32 v64, 9, v211
	v_cmp_gt_u32_e64 s[40:41], s33, v64
	s_and_b64 s[6:7], vcc, s[40:41]
	v_fmac_f32_e32 v219, 0x3e0293ee, v69
	v_cndmask_b32_e64 v67, v67, v219, s[6:7]
	v_add_u32_e32 v64, 10, v211
	v_cmp_gt_u32_e64 s[40:41], s33, v64
	s_and_b64 s[6:7], vcc, s[40:41]
	v_mov_b32_e32 v68, 0xff800000
	v_mov_b32_e32 v69, 0xff800000
	v_fmac_f32_e32 v220, 0x3e0293ee, v70
	v_cndmask_b32_e64 v69, v69, v220, s[6:7]
	v_add_u32_e32 v64, 11, v211
	v_cmp_gt_u32_e64 s[40:41], s33, v64
	s_and_b64 s[6:7], vcc, s[40:41]
	v_fmac_f32_e32 v221, 0x3e0293ee, v71
	v_cndmask_b32_e64 v68, v68, v221, s[6:7]
	v_add_u32_e32 v64, 16, v211
	v_cmp_gt_u32_e64 s[40:41], s33, v64
	s_and_b64 s[6:7], vcc, s[40:41]
	v_mov_b32_e32 v70, 0xff800000
	v_mov_b32_e32 v71, 0xff800000
	v_fmac_f32_e32 v234, 0x3e0293ee, v72
	v_cndmask_b32_e64 v71, v71, v234, s[6:7]
	v_add_u32_e32 v64, 17, v211
	v_cmp_gt_u32_e64 s[40:41], s33, v64
	s_and_b64 s[6:7], vcc, s[40:41]
	v_fmac_f32_e32 v235, 0x3e0293ee, v73
	v_cndmask_b32_e64 v70, v70, v235, s[6:7]
	v_add_u32_e32 v64, 18, v211
	v_cmp_gt_u32_e64 s[40:41], s33, v64
	s_and_b64 s[6:7], vcc, s[40:41]
	v_mov_b32_e32 v72, 0xff800000
	v_mov_b32_e32 v73, 0xff800000
	v_fmac_f32_e32 v236, 0x3e0293ee, v74
	v_cndmask_b32_e64 v73, v73, v236, s[6:7]
	v_add_u32_e32 v64, 19, v211
	v_cmp_gt_u32_e64 s[40:41], s33, v64
	s_and_b64 s[6:7], vcc, s[40:41]
	v_fmac_f32_e32 v237, 0x3e0293ee, v75
	v_cndmask_b32_e64 v72, v72, v237, s[6:7]
	v_add_u32_e32 v64, 24, v211
	v_cmp_gt_u32_e64 s[40:41], s33, v64
	s_and_b64 s[6:7], vcc, s[40:41]
	v_mov_b32_e32 v74, 0xff800000
	v_mov_b32_e32 v75, 0xff800000
	v_fmac_f32_e32 v238, 0x3e0293ee, v76
	v_cndmask_b32_e64 v75, v75, v238, s[6:7]
	v_add_u32_e32 v64, 25, v211
	v_cmp_gt_u32_e64 s[40:41], s33, v64
	s_and_b64 s[6:7], vcc, s[40:41]
	v_fmac_f32_e32 v239, 0x3e0293ee, v77
	v_cndmask_b32_e64 v74, v74, v239, s[6:7]
	v_add_u32_e32 v64, 26, v211
	v_cmp_gt_u32_e64 s[40:41], s33, v64
	s_and_b64 s[6:7], vcc, s[40:41]
	v_mov_b32_e32 v76, 0xff800000
	v_mov_b32_e32 v77, 0xff800000
	v_fmac_f32_e32 v246, 0x3e0293ee, v78
	v_cndmask_b32_e64 v77, v77, v246, s[6:7]
	v_add_u32_e32 v64, 27, v211
	v_cmp_gt_u32_e64 s[40:41], s33, v64
	s_and_b64 s[6:7], vcc, s[40:41]
	v_fmac_f32_e32 v247, 0x3e0293ee, v79
	v_cndmask_b32_e64 v76, v76, v247, s[6:7]
	s_or_b64 exec, exec, s[16:17]
	s_mov_b32 s5, 0xff800000
	v_max3_f32 v64, v197, s5, v195
	v_max3_f32 v64, v64, v199, v65
	v_max3_f32 v64, v64, v212, v67
	v_max3_f32 v64, v64, v69, v68
	v_max3_f32 v64, v64, v71, v70
	v_max3_f32 v64, v64, v73, v72
	v_max3_f32 v64, v64, v75, v74
	v_max3_f32 v64, v64, v77, v76
	v_mov_b32_e32 v66, v64
	s_nop 1
	v_permlane32_swap_b32_e32 v64, v66
	v_max3_f32 v66, v210, v64, v66
	v_sub_f32_e32 v65, v65, v66
	v_sub_f32_e32 v78, v197, v66
	v_exp_f32_e32 v197, v65
	v_sub_f32_e32 v65, v212, v66
	v_sub_f32_e32 v79, v195, v66
	v_sub_f32_e32 v195, v199, v66
	v_exp_f32_e32 v199, v65
	v_sub_f32_e32 v65, v67, v66
	v_exp_f32_e32 v67, v65
	v_sub_f32_e32 v65, v69, v66
	v_sub_f32_e32 v64, v210, v66
	v_exp_f32_e32 v210, v65
; #define MFMA32(a, b, c) __builtin_amdgcn_mfma_f32_32x32x16_bf16((a), (b), (c), 0, 0, 0)
; DI void mixA_wave_item(const Params& p, int wi, int lane, const LAS float* tb) {
;     ...
;         mx = xhalf_max(mx);
;         const float mnew = fmaxf(m, mx), alpha = __builtin_amdgcn_exp2f(m - mnew);
;         m = mnew;
;         float rs = 0.f;
; #pragma unroll
;         for (int i = 0; i < 16; ++i) { s[i] = __builtin_amdgcn_exp2f(s[i] - mnew); rs += s[i]; }
;         lsum = lsum * alpha + rs;
; #pragma unroll
;         for (int db = 0; db < 4; ++db) O[db] *= alpha;
; #pragma unroll
;         for (int sidx = 0; sidx < 2; ++sidx) {
;             const bf16x8 pf = pack8(s, sidx);
; #pragma unroll
;             for (int db = 0; db < 4; ++db) O[db] = MFMA32(vfr[sidx][db], pf, O[db]);
;         }
	v_sub_f32_e32 v65, v68, v66
	v_exp_f32_e32 v211, v65
	v_sub_f32_e32 v65, v71, v66
	v_exp_f32_e32 v212, v65
	v_sub_f32_e32 v65, v70, v66
	v_exp_f32_e32 v213, v65
	v_sub_f32_e32 v65, v73, v66
	v_exp_f32_e32 v73, v65
	v_sub_f32_e32 v65, v72, v66
	v_exp_f32_e32 v64, v64
	v_exp_f32_e32 v78, v78
	v_exp_f32_e32 v79, v79
	v_exp_f32_e32 v195, v195
	v_exp_f32_e32 v72, v65
	v_sub_f32_e32 v65, v75, v66
	v_exp_f32_e32 v75, v65
	v_sub_f32_e32 v65, v74, v66
	v_exp_f32_e32 v74, v65
	v_sub_f32_e32 v65, v77, v66
	v_exp_f32_e32 v77, v65
	v_sub_f32_e32 v65, v76, v66
	v_exp_f32_e32 v76, v65
	v_pk_mul_f32 v[62:63], v[62:63], v[64:65] op_sel_hi:[1,0]
	v_pk_mul_f32 v[60:61], v[60:61], v[64:65] op_sel_hi:[1,0]
	v_pk_mul_f32 v[58:59], v[58:59], v[64:65] op_sel_hi:[1,0]
	v_pk_mul_f32 v[56:57], v[56:57], v[64:65] op_sel_hi:[1,0]
	v_pk_mul_f32 v[54:55], v[54:55], v[64:65] op_sel_hi:[1,0]
	v_pk_mul_f32 v[52:53], v[52:53], v[64:65] op_sel_hi:[1,0]
	v_pk_mul_f32 v[50:51], v[50:51], v[64:65] op_sel_hi:[1,0]
	v_pk_mul_f32 v[48:49], v[48:49], v[64:65] op_sel_hi:[1,0]
	v_pk_mul_f32 v[46:47], v[46:47], v[64:65] op_sel_hi:[1,0]
	v_pk_mul_f32 v[44:45], v[44:45], v[64:65] op_sel_hi:[1,0]
	v_pk_mul_f32 v[42:43], v[42:43], v[64:65] op_sel_hi:[1,0]
	v_pk_mul_f32 v[40:41], v[40:41], v[64:65] op_sel_hi:[1,0]
	v_pk_mul_f32 v[38:39], v[38:39], v[64:65] op_sel_hi:[1,0]
	v_pk_mul_f32 v[36:37], v[36:37], v[64:65] op_sel_hi:[1,0]
	v_pk_mul_f32 v[34:35], v[34:35], v[64:65] op_sel_hi:[1,0]
	v_pk_mul_f32 v[32:33], v[32:33], v[64:65] op_sel_hi:[1,0]
	v_pk_mul_f32 v[30:31], v[30:31], v[64:65] op_sel_hi:[1,0]
	v_pk_mul_f32 v[28:29], v[28:29], v[64:65] op_sel_hi:[1,0]
	v_pk_mul_f32 v[26:27], v[26:27], v[64:65] op_sel_hi:[1,0]
	v_pk_mul_f32 v[24:25], v[24:25], v[64:65] op_sel_hi:[1,0]
	v_pk_mul_f32 v[22:23], v[22:23], v[64:65] op_sel_hi:[1,0]
	v_pk_mul_f32 v[20:21], v[20:21], v[64:65] op_sel_hi:[1,0]
	v_pk_mul_f32 v[18:19], v[18:19], v[64:65] op_sel_hi:[1,0]
	v_pk_mul_f32 v[16:17], v[16:17], v[64:65] op_sel_hi:[1,0]
	v_pk_mul_f32 v[14:15], v[14:15], v[64:65] op_sel_hi:[1,0]
	v_pk_mul_f32 v[12:13], v[12:13], v[64:65] op_sel_hi:[1,0]
	v_pk_mul_f32 v[10:11], v[10:11], v[64:65] op_sel_hi:[1,0]
	v_pk_mul_f32 v[8:9], v[8:9], v[64:65] op_sel_hi:[1,0]
	v_pk_mul_f32 v[6:7], v[6:7], v[64:65] op_sel_hi:[1,0]
	v_pk_mul_f32 v[4:5], v[4:5], v[64:65] op_sel_hi:[1,0]
	v_pk_mul_f32 v[2:3], v[2:3], v[64:65] op_sel_hi:[1,0]
	v_pk_mul_f32 v[0:1], v[0:1], v[64:65] op_sel_hi:[1,0]
	v_add_f32_e32 v65, 0, v78
	v_cvt_pk_bf16_f32 v68, v78, v79
	v_cvt_pk_bf16_f32 v69, v195, v197
	v_cvt_pk_bf16_f32 v70, v199, v67
	v_cvt_pk_bf16_f32 v71, v210, v211
	s_waitcnt vmcnt(5)
	v_permlane32_swap_b32_e32 v174, v176
	v_permlane32_swap_b32_e32 v175, v177
	v_permlane32_swap_b32_e32 v170, v172
	v_permlane32_swap_b32_e32 v171, v173
	v_permlane32_swap_b32_e32 v166, v168
	v_permlane32_swap_b32_e32 v167, v169
	v_add_f32_e32 v65, v79, v65
	v_add_f32_e32 v65, v195, v65
	v_mfma_f32_32x32x16_bf16 v[48:63], v[174:177], v[68:71], v[48:63]
	v_add_f32_e32 v65, v197, v65
	v_add_f32_e32 v65, v199, v65
	v_add_f32_e32 v65, v67, v65
	v_add_f32_e32 v65, v210, v65
	v_add_f32_e32 v65, v211, v65
	v_add_f32_e32 v65, v212, v65
	v_add_f32_e32 v65, v213, v65
	v_mfma_f32_32x32x16_bf16 v[32:47], v[170:173], v[68:71], v[32:47]
	v_add_f32_e32 v65, v73, v65
	v_add_f32_e32 v65, v72, v65
	v_add_f32_e32 v65, v75, v65
	v_add_f32_e32 v65, v74, v65
	v_add_f32_e32 v65, v77, v65
	v_add_f32_e32 v65, v76, v65
	s_add_i32 s4, s4, 32
	v_mfma_f32_32x32x16_bf16 v[16:31], v[166:169], v[68:71], v[16:31]
	v_fmac_f32_e32 v65, v209, v64
	v_add_u32_e32 v207, 0x80, v207
	s_cmpk_eq_i32 s4, 0xa0
	s_waitcnt vmcnt(3)
	v_permlane32_swap_b32_e32 v162, v164
	v_permlane32_swap_b32_e32 v163, v165
	v_permlane32_swap_b32_e32 v158, v160
	v_permlane32_swap_b32_e32 v159, v161
	v_mfma_f32_32x32x16_bf16 v[0:15], v[162:165], v[68:71], v[0:15]
	v_cvt_pk_bf16_f32 v68, v212, v213
	v_cvt_pk_bf16_f32 v69, v73, v72
	v_cvt_pk_bf16_f32 v70, v75, v74
	v_cvt_pk_bf16_f32 v71, v77, v76
	s_nop 1
	v_mfma_f32_32x32x16_bf16 v[48:63], v[158:161], v[68:71], v[48:63]
	s_waitcnt vmcnt(2)
	v_permlane32_swap_b32_e32 v154, v156
	v_permlane32_swap_b32_e32 v155, v157
	s_nop 1
	v_mfma_f32_32x32x16_bf16 v[32:47], v[154:157], v[68:71], v[32:47]
	s_waitcnt vmcnt(1)
	v_permlane32_swap_b32_e32 v150, v152
	v_permlane32_swap_b32_e32 v151, v153
	s_nop 1
	v_mfma_f32_32x32x16_bf16 v[16:31], v[150:153], v[68:71], v[16:31]
	s_waitcnt vmcnt(0)
	v_permlane32_swap_b32_e32 v146, v148
	v_permlane32_swap_b32_e32 v147, v149
	s_nop 1
	v_mfma_f32_32x32x16_bf16 v[0:15], v[146:149], v[68:71], v[0:15]
	s_cbranch_scc1 .LBB0_596
	v_mov_b32_e32 v209, v65
	v_mov_b32_e32 v210, v66
	s_branch .LBB0_560
